# recur phase: blocks >= 256 sleep ~6k cycles before first queue pull so that one block per CU takes the long chain items
# speedup vs baseline: 1.0150x; 1.0150x over previous
.LBB0_285:
	s_or_b64 exec, exec, s[0:1]
	v_readlane_b32 s4, v254, 3
	v_readlane_b32 s18, v254, 17
	v_readlane_b32 s19, v254, 18
	s_add_u32 s0, s18, 0x5790000
	v_readlane_b32 s5, v254, 4
	v_readlane_b32 s6, v254, 5
	v_readlane_b32 s7, v254, 6
	v_readlane_b32 s8, v254, 7
	v_readlane_b32 s9, v254, 8
	v_readlane_b32 s10, v254, 9
	v_readlane_b32 s11, v254, 10
	v_readlane_b32 s12, v254, 11
	v_readlane_b32 s13, v254, 12
	v_readlane_b32 s14, v254, 13
	v_readlane_b32 s15, v254, 14
	v_readlane_b32 s16, v254, 15
	v_readlane_b32 s17, v254, 16
	v_writelane_b32 v254, s0, 62
	s_addc_u32 s0, s19, 0
	s_add_u32 s26, s74, 0x1000
	s_addc_u32 s27, s75, 0
	v_writelane_b32 v254, s0, 63
	s_add_u32 s0, s74, 0x1200
	s_addc_u32 s1, s75, 0
	s_mov_b32 s87, 0
	v_writelane_b32 v255, s0, 0
	v_mov_b32_e32 v28, 0
	s_movk_i32 s7, 0x1e20
	v_writelane_b32 v255, s1, 1
	s_add_u32 s0, s74, 0x1400
	s_addc_u32 s1, s75, 0
	v_writelane_b32 v255, s0, 2
	s_movk_i32 s24, 0x1000
	s_mov_b32 s90, 0xbfb8aa3b
	v_writelane_b32 v255, s1, 3
	s_add_u32 s0, s74, 0x1600
	s_addc_u32 s1, s75, 0
	v_writelane_b32 v255, s0, 4
	s_mov_b32 s91, 0x800000
	s_mov_b32 s92, 0x3f317217
	v_writelane_b32 v255, s1, 5
	s_add_u32 s0, s74, 0x1800
	s_addc_u32 s1, s75, 0
	v_writelane_b32 v255, s0, 6
	s_mov_b32 s93, 0x7f800000
	s_mov_b32 s6, 0x3e3504f3
	v_writelane_b32 v255, s1, 7
	s_add_u32 s0, s74, 0x1a00
	s_addc_u32 s1, s75, 0
	v_writelane_b32 v255, s0, 8
	s_movk_i32 s94, 0x800
	v_mov_b32_e32 v71, 0x42800000
	v_writelane_b32 v255, s1, 9
	s_add_u32 s0, s74, 0x1c00
	s_addc_u32 s1, s75, 0
	v_writelane_b32 v255, s0, 10
	v_mov_b32_e32 v72, 0x1800
	v_mov_b32_e32 v73, 0x1600
	v_writelane_b32 v255, s1, 11
	s_add_u32 s0, s74, 0x1e00
	s_addc_u32 s1, s75, 0
	v_writelane_b32 v255, s0, 12
	v_mov_b32_e32 v74, 0x3e000000
	v_mov_b32_e32 v75, 0x41b17218
	v_writelane_b32 v255, s1, 13
	s_add_u32 s0, s18, 0x4790000
	v_writelane_b32 v255, s0, 14
	s_addc_u32 s0, s19, 0
	v_writelane_b32 v255, s0, 15
	s_add_u32 s0, s18, 0x7090000
	v_writelane_b32 v255, s0, 16
	s_addc_u32 s0, s19, 0
	v_writelane_b32 v255, s0, 17
	s_add_u32 s0, s18, 0x5f90000
	v_writelane_b32 v255, s0, 18
	s_addc_u32 s0, s19, 0
	s_add_u32 s31, s18, 0x4690000
	v_writelane_b32 v255, s0, 19
	s_addc_u32 s0, s19, 0
	v_writelane_b32 v255, s0, 20
	s_add_u32 s0, s18, 0x4500000
	v_writelane_b32 v255, s0, 22
	s_addc_u32 s0, s19, 0
	v_writelane_b32 v255, s0, 24
	s_add_u32 s0, s18, 0x4400000
	v_writelane_b32 v255, s0, 26
	s_addc_u32 s0, s19, 0
	v_writelane_b32 v255, s0, 42
	s_add_i32 s3, 0, 0x10010
	s_add_i32 s0, 0, 0x3000
	v_writelane_b32 v255, s0, 44
	v_mov_b32_e32 v70, s3
	v_mov_b32_e32 v76, 0xc00
	v_mov_b32_e32 v77, 0xb00
	v_mov_b32_e32 v78, 0x1000
	s_waitcnt lgkmcnt(0)
	s_barrier
	s_cmp_lt_u32 s2, 256
	s_cbranch_scc1 .Lnosleep_0
	s_sleep 100
.Lnosleep_0:
	s_branch .LBB0_289

.LBB0_1268:
	s_or_b64 exec, exec, s[0:1]
	v_readlane_b32 s52, v255, 26
	v_readlane_b32 s58, v255, 32
	v_readlane_b32 s59, v255, 33
	s_add_u32 s92, s58, 0x2000
	s_addc_u32 s93, s59, 0
	s_add_u32 s0, s58, 0x3000
	s_addc_u32 s1, s59, 0
	v_writelane_b32 v254, s0, 37
	v_readlane_b32 s53, v255, 27
	v_readlane_b32 s54, v255, 28
	v_writelane_b32 v254, s1, 38
	s_add_u32 s0, s58, 0x2200
	s_addc_u32 s1, s59, 0
	v_writelane_b32 v254, s0, 58
	v_readlane_b32 s55, v255, 29
	v_readlane_b32 s56, v255, 30
	v_writelane_b32 v254, s1, 59
	s_add_u32 s0, s58, 0x3200
	s_addc_u32 s1, s59, 0
	v_readlane_b32 s57, v255, 31
	v_readlane_b32 s60, v255, 34
	v_readlane_b32 s61, v255, 35
	v_readlane_b32 s62, v255, 36
	v_readlane_b32 s63, v255, 37
	v_readlane_b32 s64, v255, 38
	v_readlane_b32 s65, v255, 39
	v_readlane_b32 s66, v255, 40
	v_readlane_b32 s67, v255, 41
	v_writelane_b32 v255, s0, 20
	s_mov_b32 s11, 0
	v_mov_b32_e32 v28, 0
	v_writelane_b32 v255, s1, 21
	s_add_u32 s0, s58, 0x2400
	s_addc_u32 s1, s59, 0
	v_writelane_b32 v255, s0, 22
	s_movk_i32 s3, 0x1e20
	s_movk_i32 s94, 0x1000
	v_writelane_b32 v255, s1, 23
	s_add_u32 s0, s58, 0x3400
	s_addc_u32 s1, s59, 0
	v_writelane_b32 v255, s0, 24
	s_mov_b32 s95, 0xbfb8aa3b
	s_mov_b32 s52, 0x800000
	v_writelane_b32 v255, s1, 25
	s_add_u32 s0, s58, 0x2600
	s_addc_u32 s1, s59, 0
	v_writelane_b32 v254, s0, 60
	s_mov_b32 s53, 0x3f317217
	s_mov_b32 s54, 0x7f800000
	v_writelane_b32 v254, s1, 61
	s_add_u32 s0, s58, 0x3600
	s_addc_u32 s1, s59, 0
	v_writelane_b32 v255, s0, 0
	s_mov_b32 s4, 0x3e3504f3
	s_movk_i32 s55, 0x800
	v_writelane_b32 v255, s1, 1
	s_add_u32 s0, s58, 0x2800
	s_addc_u32 s1, s59, 0
	v_writelane_b32 v255, s0, 2
	v_mov_b32_e32 v73, 0x42800000
	v_mov_b32_e32 v74, 0x1800
	v_writelane_b32 v255, s1, 3
	s_add_u32 s0, s58, 0x3800
	s_addc_u32 s1, s59, 0
	v_writelane_b32 v255, s0, 4
	v_mov_b32_e32 v75, 0x1600
	v_mov_b32_e32 v76, 0x3e000000
	v_writelane_b32 v255, s1, 5
	s_add_u32 s0, s58, 0x2a00
	s_addc_u32 s1, s59, 0
	v_writelane_b32 v255, s0, 6
	v_mov_b32_e32 v77, 0x41b17218
	v_mov_b32_e32 v78, 0xc00
	v_writelane_b32 v255, s1, 7
	s_add_u32 s0, s58, 0x3a00
	s_addc_u32 s1, s59, 0
	v_writelane_b32 v255, s0, 8
	v_mov_b32_e32 v79, 0xb00
	v_mov_b32_e32 v80, 0x1000
	v_writelane_b32 v255, s1, 9
	s_add_u32 s0, s58, 0x2c00
	s_addc_u32 s1, s59, 0
	v_writelane_b32 v255, s0, 10
	s_waitcnt lgkmcnt(0)
	s_barrier
	v_writelane_b32 v255, s1, 11
	s_add_u32 s0, s58, 0x3c00
	s_addc_u32 s1, s59, 0
	s_add_u32 s96, s58, 0x2e00
	s_addc_u32 s97, s59, 0
	s_add_u32 s90, s58, 0x3e00
	v_writelane_b32 v255, s0, 12
	s_addc_u32 s91, s59, 0
	s_add_i32 s5, 0, 0x10010
	v_writelane_b32 v255, s1, 13
	v_mov_b32_e32 v72, s5
	s_cmp_lt_u32 s2, 256
	s_cbranch_scc1 .Lnosleep_1
	s_sleep 100
